# SBA attention QK: all eight K-fragment LDS reads issued up front into dead registers, MFMAs in two interleaved chains (no late LDS round trips behind the first MFMAs)
# baseline (speedup 1.0000x reference)
; __device__ __forceinline__ void phase_sba_attn(const Params& p, u16* sm) {
;     ...
;       const bool wave_idle = (kt * 64 >= qt * 128 + wave * 16 + 15) || (__ballot(carry >= -150.1f) == 0ull);
;       if (!wave_idle) {
;       f32x4 s[4];
; #pragma unroll
;       for (int mt = 0; mt < 4; ++mt) {
;         s[mt] = (f32x4){0.f, 0.f, 0.f, 0.f};
; #pragma unroll
;         for (int ks = 0; ks < 2; ++ks) {
;           bf16x8 kf = *(const bf16x8*)(sK + (mt * 16 + fr) * LDSP + ks * 32 + fq * 8);
;           s[mt] = mfma16(kf, qf[ks], s[mt]);
;         }
;       }
.LBB0_329:
	s_add_i32 s9, s20, 64
	v_cmp_lt_u32_e32 vcc, s9, v114
	s_waitcnt lgkmcnt(0)
	s_barrier
	s_and_saveexec_b64 s[26:27], vcc
	s_cbranch_execz .LBB0_336
	v_cmp_le_f32_e32 vcc, s1, v0
	s_cbranch_vccz .LBB0_336
	v_add_u32_e32 v2, s8, v97
	v_add_u32_e32 v115, v2, v98
	ds_read_b128 v[44:47], v115
	ds_read_b128 v[48:51], v115 offset:64
	ds_read_b128 v[52:55], v115 offset:2304
	ds_read_b128 v[78:81], v115 offset:2368
	ds_read_b128 v[82:85], v115 offset:4608
	ds_read_b128 v[86:89], v115 offset:4672
	ds_read_b128 v[90:93], v115 offset:6912
	ds_read_b128 v[116:119], v115 offset:6976
	s_add_i32 s8, s20, 0x7f
	v_cmp_lt_u32_e32 vcc, s8, v71
	v_cmp_ge_u32_e64 s[8:9], s8, v71
	s_waitcnt lgkmcnt(5)
	v_mfma_f32_16x16x32_bf16 v[56:59], v[44:47], v[12:15], 0
	v_mfma_f32_16x16x32_bf16 v[52:55], v[52:55], v[12:15], 0
	s_waitcnt lgkmcnt(4)
	v_mfma_f32_16x16x32_bf16 v[56:59], v[48:51], v[16:19], v[56:59]
	v_mfma_f32_16x16x32_bf16 v[52:55], v[78:81], v[16:19], v[52:55]
	s_waitcnt lgkmcnt(1)
	v_mfma_f32_16x16x32_bf16 v[48:51], v[82:85], v[12:15], 0
	v_mfma_f32_16x16x32_bf16 v[44:47], v[90:93], v[12:15], 0
	s_waitcnt lgkmcnt(0)
	v_mfma_f32_16x16x32_bf16 v[48:51], v[86:89], v[16:19], v[48:51]
	v_mfma_f32_16x16x32_bf16 v[44:47], v[116:119], v[16:19], v[44:47]
	s_and_saveexec_b64 s[10:11], s[8:9]
	s_xor_b64 s[10:11], exec, s[10:11]
	s_cbranch_execz .LBB0_333
; __device__ __forceinline__ void phase_sba_attn(const Params& p, u16* sm) {
;     ...
;       if (tile_masked) {
;         vmask = 0;
; #pragma unroll
;         for (int mt = 0; mt < 4; ++mt)
; #pragma unroll
;           for (int j = 0; j < 4; ++j) {
;             const float z = s[mt][j] * SBA_C;
;             const int key = kt * 64 + 32 * (mt >> 1) + 8 * fq + 4 * (mt & 1) + j;
;             const bool valid = key < myq;
;             const float e = __builtin_amdgcn_exp2f(-fabsf(z));
;             const float sp = fmaxf(z, 0.f) + __builtin_amdgcn_logf(1.f + e);
;             L[mt][j] = valid ? -sp : 0.f;
;             lb[mt][j] = z - sp;
;             vmask |= (valid ? 1u : 0u) << (mt * 4 + j);
;           }
	v_pk_mul_f32 v[2:3], v[56:57], s[22:23] op_sel_hi:[1,0]
	v_add_u32_e32 v92, s20, v60
	v_exp_f32_e64 v78, -|v2|
	v_exp_f32_e64 v79, -|v3|
	v_add_u32_e32 v80, 64, v92
	v_max_f32_e32 v2, 0, v2
	v_add_f32_e32 v78, 1.0, v78
	v_add_f32_e32 v79, 1.0, v79
	v_log_f32_e32 v78, v78
	v_log_f32_e32 v79, v79
	v_max_f32_e32 v3, 0, v3
	v_cmp_lt_u32_e64 s[8:9], v80, v113
	v_add_u32_e32 v81, 0x41, v92
	v_pk_add_f32 v[78:79], v[2:3], v[78:79]
	v_cndmask_b32_e64 v80, 0, 1, s[8:9]
	v_cndmask_b32_e64 v2, 0, -v78, s[8:9]
	v_cmp_lt_u32_e64 s[8:9], v81, v113
	v_add_u32_e32 v83, 0x42, v92
	v_add_u32_e32 v84, 0x43, v92
	v_cndmask_b32_e64 v3, 0, -v79, s[8:9]
	v_pk_fma_f32 v[78:79], v[56:57], s[22:23], v[78:79] op_sel_hi:[1,0,1] neg_lo:[0,0,1] neg_hi:[0,0,1]
	v_cndmask_b32_e64 v56, 0, 2, s[8:9]
	v_or_b32_e32 v82, v56, v80
	v_pk_mul_f32 v[56:57], v[58:59], s[22:23] op_sel_hi:[1,0]
	v_cmp_lt_u32_e64 s[8:9], v83, v113
	v_exp_f32_e64 v80, -|v56|
	v_exp_f32_e64 v81, -|v57|
	v_max_f32_e32 v56, 0, v56
	v_max_f32_e32 v57, 0, v57
	v_add_f32_e32 v80, 1.0, v80
	v_add_f32_e32 v81, 1.0, v81
	v_log_f32_e32 v80, v80
	v_log_f32_e32 v81, v81
	v_cndmask_b32_e64 v83, 0, 4, s[8:9]
	v_pk_add_f32 v[56:57], v[56:57], v[80:81]
	s_nop 0
	v_cndmask_b32_e64 v116, 0, -v56, s[8:9]
	v_cmp_lt_u32_e64 s[8:9], v84, v113
	v_pk_fma_f32 v[80:81], v[58:59], s[22:23], v[56:57] op_sel_hi:[1,0,1] neg_lo:[0,0,1] neg_hi:[0,0,1]
	s_nop 0
	v_cndmask_b32_e64 v56, 0, 8, s[8:9]
	v_cndmask_b32_e64 v117, 0, -v57, s[8:9]
	v_or3_b32 v84, v82, v83, v56
	v_pk_mul_f32 v[56:57], v[52:53], s[22:23] op_sel_hi:[1,0]
	v_add_u32_e32 v82, 0x44, v92
	v_exp_f32_e64 v58, -|v56|
	v_exp_f32_e64 v59, -|v57|
	v_max_f32_e32 v56, 0, v56
	v_max_f32_e32 v57, 0, v57
	v_add_f32_e32 v58, 1.0, v58
	v_add_f32_e32 v59, 1.0, v59
	v_log_f32_e32 v58, v58
	v_log_f32_e32 v59, v59
	v_cmp_lt_u32_e64 s[8:9], v82, v113
	v_add_u32_e32 v82, 0x45, v92
	v_pk_add_f32 v[56:57], v[56:57], v[58:59]
	v_cndmask_b32_e64 v85, 0, 16, s[8:9]
	v_cndmask_b32_e64 v118, 0, -v56, s[8:9]
	v_cmp_lt_u32_e64 s[8:9], v82, v113
	v_pk_fma_f32 v[82:83], v[52:53], s[22:23], v[56:57] op_sel_hi:[1,0,1] neg_lo:[0,0,1] neg_hi:[0,0,1]
	v_add_u32_e32 v59, 0x46, v92
	v_cndmask_b32_e64 v52, 0, 32, s[8:9]
	v_or3_b32 v58, v84, v85, v52
	v_pk_mul_f32 v[52:53], v[54:55], s[22:23] op_sel_hi:[1,0]
	v_cndmask_b32_e64 v119, 0, -v57, s[8:9]
	v_exp_f32_e64 v56, -|v52|
	v_exp_f32_e64 v57, -|v53|
	v_max_f32_e32 v52, 0, v52
	v_max_f32_e32 v53, 0, v53
	v_add_f32_e32 v56, 1.0, v56
	v_add_f32_e32 v57, 1.0, v57
	v_log_f32_e32 v56, v56
	v_log_f32_e32 v57, v57
	v_cmp_lt_u32_e64 s[8:9], v59, v113
	v_add_u32_e32 v84, 0x47, v92
	v_pk_add_f32 v[52:53], v[52:53], v[56:57]
	v_cndmask_b32_e64 v59, 0, 64, s[8:9]
	v_cndmask_b32_e64 v120, 0, -v52, s[8:9]
	v_cmp_lt_u32_e64 s[8:9], v84, v113
	v_pk_fma_f32 v[84:85], v[54:55], s[22:23], v[52:53] op_sel_hi:[1,0,1] neg_lo:[0,0,1] neg_hi:[0,0,1]
	v_add_u32_e32 v57, 0x60, v92
	v_cndmask_b32_e64 v52, 0, v101, s[8:9]
	v_cndmask_b32_e64 v121, 0, -v53, s[8:9]
	v_or3_b32 v56, v58, v59, v52
	v_pk_mul_f32 v[52:53], v[48:49], s[22:23] op_sel_hi:[1,0]
	v_cmp_lt_u32_e64 s[8:9], v57, v113
	v_exp_f32_e64 v54, -|v52|
	v_exp_f32_e64 v55, -|v53|
	v_max_f32_e32 v52, 0, v52
	v_max_f32_e32 v53, 0, v53
	v_add_f32_e32 v54, 1.0, v54
	v_add_f32_e32 v55, 1.0, v55
	v_log_f32_e32 v54, v54
	v_log_f32_e32 v55, v55
	v_add_u32_e32 v58, 0x61, v92
	v_cndmask_b32_e64 v57, 0, v102, s[8:9]
	v_pk_add_f32 v[52:53], v[52:53], v[54:55]
	s_nop 0
	v_cndmask_b32_e64 v123, 0, -v52, s[8:9]
	v_cmp_lt_u32_e64 s[8:9], v58, v113
	v_pk_fma_f32 v[86:87], v[48:49], s[22:23], v[52:53] op_sel_hi:[1,0,1] neg_lo:[0,0,1] neg_hi:[0,0,1]
	v_add_u32_e32 v55, 0x62, v92
	v_cndmask_b32_e64 v48, 0, v103, s[8:9]
	v_or3_b32 v54, v56, v57, v48
	v_pk_mul_f32 v[48:49], v[50:51], s[22:23] op_sel_hi:[1,0]
	v_cndmask_b32_e64 v124, 0, -v53, s[8:9]
	v_exp_f32_e64 v52, -|v48|
	v_exp_f32_e64 v53, -|v49|
	v_max_f32_e32 v48, 0, v48
	v_max_f32_e32 v49, 0, v49
	v_add_f32_e32 v52, 1.0, v52
	v_add_f32_e32 v53, 1.0, v53
	v_log_f32_e32 v52, v52
	v_log_f32_e32 v53, v53
	v_cmp_lt_u32_e64 s[8:9], v55, v113
	v_add_u32_e32 v56, 0x63, v92
	v_pk_add_f32 v[48:49], v[48:49], v[52:53]
	v_cndmask_b32_e64 v55, 0, v104, s[8:9]
	v_cndmask_b32_e64 v125, 0, -v48, s[8:9]
	v_cmp_lt_u32_e64 s[8:9], v56, v113
	v_pk_fma_f32 v[88:89], v[50:51], s[22:23], v[48:49] op_sel_hi:[1,0,1] neg_lo:[0,0,1] neg_hi:[0,0,1]
	v_add_u32_e32 v53, 0x64, v92
	v_cndmask_b32_e64 v48, 0, v105, s[8:9]
	v_cndmask_b32_e64 v126, 0, -v49, s[8:9]
	v_or3_b32 v52, v54, v55, v48
	v_pk_mul_f32 v[48:49], v[44:45], s[22:23] op_sel_hi:[1,0]
	v_cmp_lt_u32_e64 s[8:9], v53, v113
	v_exp_f32_e64 v50, -|v48|
	v_exp_f32_e64 v51, -|v49|
	v_max_f32_e32 v48, 0, v48
	v_max_f32_e32 v49, 0, v49
	v_add_f32_e32 v50, 1.0, v50
	v_add_f32_e32 v51, 1.0, v51
	v_log_f32_e32 v50, v50
	v_log_f32_e32 v51, v51
	v_add_u32_e32 v54, 0x65, v92
	v_cndmask_b32_e64 v53, 0, v106, s[8:9]
	v_pk_add_f32 v[48:49], v[48:49], v[50:51]
	s_nop 0
	v_cndmask_b32_e64 v127, 0, -v48, s[8:9]
	v_cmp_lt_u32_e64 s[8:9], v54, v113
	v_pk_fma_f32 v[90:91], v[44:45], s[22:23], v[48:49] op_sel_hi:[1,0,1] neg_lo:[0,0,1] neg_hi:[0,0,1]
	v_add_u32_e32 v51, 0x66, v92
	v_cndmask_b32_e64 v44, 0, v107, s[8:9]
	v_or3_b32 v50, v52, v53, v44
	v_pk_mul_f32 v[44:45], v[46:47], s[22:23] op_sel_hi:[1,0]
	v_cndmask_b32_e64 v128, 0, -v49, s[8:9]
	v_exp_f32_e64 v48, -|v44|
	v_exp_f32_e64 v49, -|v45|
	v_max_f32_e32 v44, 0, v44
	v_max_f32_e32 v45, 0, v45
	v_add_f32_e32 v48, 1.0, v48
	v_add_f32_e32 v49, 1.0, v49
	v_log_f32_e32 v48, v48
	v_log_f32_e32 v49, v49
	v_cmp_lt_u32_e64 s[8:9], v51, v113
	v_add_u32_e32 v52, 0x67, v92
	v_pk_add_f32 v[44:45], v[44:45], v[48:49]
	v_cndmask_b32_e64 v51, 0, v108, s[8:9]
	v_cndmask_b32_e64 v130, 0, -v44, s[8:9]
	v_cmp_lt_u32_e64 s[8:9], v52, v113
	v_pk_fma_f32 v[92:93], v[46:47], s[22:23], v[44:45] op_sel_hi:[1,0,1] neg_lo:[0,0,1] neg_hi:[0,0,1]
	s_nop 0
	v_cndmask_b32_e64 v44, 0, v109, s[8:9]
	v_cndmask_b32_e64 v129, 0, -v45, s[8:9]
	v_or3_b32 v122, v50, v51, v44
